# strategy 7: packed v_pk_mul/add/fma_f32 in the SSD chunk loop split into scalar fp32 ops (bit-identical)
# speedup vs baseline: 1.0030x; 1.0030x over previous
.LBB0_314:
	s_nop 9
	v_bfe_u32 v34, v2, 16, 1
	s_movk_i32 s37, 0x7fff
	v_add3_u32 v34, v2, v34, s37
	ds_write_b16_d16_hi v240, v34
	v_bfe_u32 v34, v3, 16, 1
	v_add3_u32 v34, v3, v34, s37
	ds_write_b16_d16_hi v240, v34 offset:272
	v_bfe_u32 v34, v4, 16, 1
	v_add3_u32 v34, v4, v34, s37
	ds_write_b16_d16_hi v240, v34 offset:544
	v_bfe_u32 v34, v5, 16, 1
	v_add3_u32 v34, v5, v34, s37
	ds_write_b16_d16_hi v240, v34 offset:816
	v_bfe_u32 v34, v6, 16, 1
	v_add3_u32 v34, v6, v34, s37
	ds_write_b16_d16_hi v240, v34 offset:2176
	v_bfe_u32 v34, v7, 16, 1
	v_add3_u32 v34, v7, v34, s37
	ds_write_b16_d16_hi v240, v34 offset:2448
	v_bfe_u32 v34, v8, 16, 1
	v_add3_u32 v34, v8, v34, s37
	ds_write_b16_d16_hi v240, v34 offset:2720
	v_bfe_u32 v34, v9, 16, 1
	v_add3_u32 v34, v9, v34, s37
	ds_write_b16_d16_hi v240, v34 offset:2992
	v_bfe_u32 v34, v10, 16, 1
	v_add3_u32 v34, v10, v34, s37
	ds_write_b16_d16_hi v240, v34 offset:4352
	v_bfe_u32 v34, v11, 16, 1
	v_add3_u32 v34, v11, v34, s37
	s_waitcnt vmcnt(3)
	v_lshlrev_b32_e32 v36, 16, v142
	v_and_b32_e32 v37, 0xffff0000, v142
	s_mov_b32 s40, 0xbfb8aa3b
	ds_write_b16_d16_hi v240, v34 offset:4624
	v_bfe_u32 v34, v12, 16, 1
	v_lshlrev_b32_e32 v38, 16, v143
	v_and_b32_e32 v39, 0xffff0000, v143
	v_mul_f32_e32 v40, s40, v36
	v_mul_f32_e32 v41, s40, v37
	v_add3_u32 v34, v12, v34, s37
	v_mul_f32_e32 v42, s40, v38
	v_mul_f32_e32 v43, s40, v39
	v_exp_f32_e32 v40, v40
	v_exp_f32_e32 v41, v41
	ds_write_b16_d16_hi v240, v34 offset:4896
	v_bfe_u32 v34, v13, 16, 1
	v_exp_f32_e32 v42, v42
	v_exp_f32_e32 v43, v43
	v_add3_u32 v34, v13, v34, s37
	ds_write_b16_d16_hi v240, v34 offset:5168
	v_bfe_u32 v34, v14, 16, 1
	v_add3_u32 v34, v14, v34, s37
	v_add_f32_e32 v40, 1.0, v40
	v_add_f32_e32 v41, 1.0, v41
	ds_write_b16_d16_hi v240, v34 offset:6528
	v_bfe_u32 v34, v15, 16, 1
	v_add_f32_e32 v42, 1.0, v42
	v_add_f32_e32 v43, 1.0, v43
	v_rcp_f32_e32 v40, v40
	v_rcp_f32_e32 v41, v41
	v_add3_u32 v34, v15, v34, s37
	v_rcp_f32_e32 v42, v42
	v_rcp_f32_e32 v43, v43
	ds_write_b16_d16_hi v240, v34 offset:6800
	v_bfe_u32 v34, v16, 16, 1
	v_add3_u32 v34, v16, v34, s37
	ds_write_b16_d16_hi v240, v34 offset:7072
	v_bfe_u32 v34, v17, 16, 1
	v_mul_f32_e32 v36, v40, v36
	v_mul_f32_e32 v37, v41, v37
	v_add3_u32 v34, v17, v34, s37
	v_mul_f32_e32 v18, v36, v18
	v_mul_f32_e32 v19, v37, v19
	v_mul_f32_e32 v36, v42, v38
	v_mul_f32_e32 v37, v43, v39
	ds_write_b16_d16_hi v240, v34 offset:7344
	v_lshlrev_b64 v[34:35], 12, v[144:145]
	v_mul_f32_e32 v20, v36, v20
	v_mul_f32_e32 v21, v37, v21
	v_cvt_pk_bf16_f32 v18, v18, v19
	s_cmp_lg_u32 s33, 32
	v_cvt_pk_bf16_f32 v19, v20, v21
	v_lshl_add_u64 v[20:21], v[134:135], 0, v[34:35]
	global_store_dwordx2 v[20:21], v[18:19], off
	s_waitcnt vmcnt(3)
	v_lshlrev_b32_e32 v18, 16, v140
	v_and_b32_e32 v19, 0xffff0000, v140
	v_lshlrev_b32_e32 v34, 16, v141
	v_and_b32_e32 v35, 0xffff0000, v141
	v_mul_f32_e32 v36, s40, v18
	v_mul_f32_e32 v37, s40, v19
	v_mul_f32_e32 v38, s40, v34
	v_mul_f32_e32 v39, s40, v35
	v_exp_f32_e32 v36, v36
	v_exp_f32_e32 v37, v37
	v_exp_f32_e32 v38, v38
	v_exp_f32_e32 v39, v39
	s_mov_b32 s44, s33
	v_add_f32_e32 v36, 1.0, v36
	v_add_f32_e32 v37, 1.0, v37
	v_add_f32_e32 v38, 1.0, v38
	v_add_f32_e32 v39, 1.0, v39
	v_rcp_f32_e32 v36, v36
	v_rcp_f32_e32 v37, v37
	v_rcp_f32_e32 v38, v38
	v_rcp_f32_e32 v39, v39
	v_mul_f32_e32 v18, v36, v18
	v_mul_f32_e32 v19, v37, v19
	s_nop 0
	v_mul_f32_e32 v18, v18, v22
	v_mul_f32_e32 v19, v19, v23
	v_mul_f32_e32 v22, v38, v34
	v_mul_f32_e32 v23, v39, v35
	v_cvt_pk_bf16_f32 v18, v18, v19
	s_nop 0
	v_mul_f32_e32 v22, v22, v24
	v_mul_f32_e32 v23, v23, v25
	s_nop 0
	v_cvt_pk_bf16_f32 v19, v22, v23
	global_store_dwordx2 v[20:21], v[18:19], off offset:16
	s_waitcnt vmcnt(3)
	v_lshlrev_b32_e32 v18, 16, v138
	v_and_b32_e32 v19, 0xffff0000, v138
	v_lshlrev_b32_e32 v22, 16, v139
	v_and_b32_e32 v23, 0xffff0000, v139
	v_mul_f32_e32 v24, s40, v18
	v_mul_f32_e32 v25, s40, v19
	v_mul_f32_e32 v34, s40, v22
	v_mul_f32_e32 v35, s40, v23
	v_exp_f32_e32 v24, v24
	v_exp_f32_e32 v25, v25
	v_exp_f32_e32 v34, v34
	v_exp_f32_e32 v35, v35
	v_add_f32_e32 v24, 1.0, v24
	v_add_f32_e32 v25, 1.0, v25
	s_nop 0
	v_rcp_f32_e32 v24, v24
	v_add_f32_e32 v34, 1.0, v34
	v_add_f32_e32 v35, 1.0, v35
	v_rcp_f32_e32 v25, v25
	v_rcp_f32_e32 v34, v34
	v_rcp_f32_e32 v35, v35
	v_mul_f32_e32 v18, v24, v18
	v_mul_f32_e32 v19, v25, v19
	s_nop 0
	v_mul_f32_e32 v18, v18, v26
	v_mul_f32_e32 v19, v19, v27
	v_mul_f32_e32 v22, v34, v22
	v_mul_f32_e32 v23, v35, v23
	v_cvt_pk_bf16_f32 v18, v18, v19
	s_nop 0
	v_mul_f32_e32 v22, v22, v28
	v_mul_f32_e32 v23, v23, v29
	s_nop 0
	v_cvt_pk_bf16_f32 v19, v22, v23
	global_store_dwordx2 v[20:21], v[18:19], off offset:32
	s_waitcnt vmcnt(3)
	v_lshlrev_b32_e32 v18, 16, v136
	v_and_b32_e32 v19, 0xffff0000, v136
	v_lshlrev_b32_e32 v22, 16, v137
	v_and_b32_e32 v23, 0xffff0000, v137
	v_mul_f32_e32 v24, s40, v18
	v_mul_f32_e32 v25, s40, v19
	v_mul_f32_e32 v26, s40, v22
	v_mul_f32_e32 v27, s40, v23
	v_exp_f32_e32 v24, v24
	v_exp_f32_e32 v25, v25
	v_exp_f32_e32 v26, v26
	v_exp_f32_e32 v27, v27
	v_add_f32_e32 v24, 1.0, v24
	v_add_f32_e32 v25, 1.0, v25
	s_nop 0
	v_rcp_f32_e32 v24, v24
	v_add_f32_e32 v26, 1.0, v26
	v_add_f32_e32 v27, 1.0, v27
	v_rcp_f32_e32 v25, v25
	v_rcp_f32_e32 v26, v26
	v_rcp_f32_e32 v27, v27
	v_mul_f32_e32 v18, v24, v18
	v_mul_f32_e32 v19, v25, v19
	s_nop 0
	v_mul_f32_e32 v18, v18, v30
	v_mul_f32_e32 v19, v19, v31
	v_mul_f32_e32 v22, v26, v22
	v_mul_f32_e32 v23, v27, v23
	v_cvt_pk_bf16_f32 v18, v18, v19
	s_nop 0
	v_mul_f32_e32 v22, v22, v32
	v_mul_f32_e32 v23, v23, v33
	s_nop 0
	v_cvt_pk_bf16_f32 v19, v22, v23
	global_store_dwordx2 v[20:21], v[18:19], off offset:48
	s_cbranch_scc0 .LBB0_305

.LBB0_320:
	s_or_b64 exec, exec, s[42:43]
	v_and_b32_e32 v24, 64, v197
	v_mul_f32_e32 v20, v128, v18
	v_mul_f32_e32 v21, v129, v19
	v_add_f32_e32 v21, v20, v21
	v_mov_b32_e32 v23, v21
	s_nop 1
	v_add_f32_dpp v23, v23, v23 row_shr:1 row_mask:0xf bank_mask:0xf
	s_nop 1
	v_add_f32_dpp v23, v23, v23 row_shr:2 row_mask:0xf bank_mask:0xf
	s_nop 1
	v_add_f32_dpp v23, v23, v23 row_shr:4 row_mask:0xf bank_mask:0xf
	s_nop 1
	v_add_f32_dpp v23, v23, v23 row_shr:8 row_mask:0xf bank_mask:0xf
	s_nop 1
	v_add_f32_dpp v23, v23, v23 row_bcast:15 row_mask:0xa bank_mask:0xf
	s_nop 1
	v_add_f32_dpp v23, v23, v23 row_bcast:31 row_mask:0xc bank_mask:0xf
	s_nop 1
	v_sub_f32_e32 v21, v23, v21
	v_add_f32_e32 v22, v20, v21
	v_bfrev_b32_e32 v20, 0.5
	v_lshl_or_b32 v20, v197, 2, v20
	ds_bpermute_b32 v21, v20, v23
	ds_write_b64 v148, v[18:19]
	ds_write_b64 v149, v[22:23]
	s_waitcnt lgkmcnt(2)
	v_sub_f32_e32 v20, v21, v22
	v_sub_f32_e32 v21, v21, v23
	v_exp_f32_e32 v20, v20
	v_exp_f32_e32 v21, v21
	s_nop 0
	v_mul_f32_e32 v20, v18, v20
	v_mul_f32_e32 v21, v19, v21
	ds_write_b64 v150, v[20:21]
	v_exp_f32_e32 v20, v22
	v_exp_f32_e32 v21, v23
	ds_write_b64 v151, v[20:21]
	v_or_b32_e32 v20, v24, v152
	v_lshlrev_b32_e32 v20, 2, v20
	ds_bpermute_b32 v20, v20, v23
	s_waitcnt lgkmcnt(0)
	v_sub_f32_e32 v21, v20, v22
	v_exp_f32_e32 v22, v21
	v_sub_f32_e32 v21, v20, v23
	v_exp_f32_e32 v23, v21
	s_nop 0
	v_mul_f32_e32 v18, v18, v22
	v_mul_f32_e32 v19, v19, v23
	ds_write_b64 v153, v[18:19]
	s_and_b64 exec, exec, s[50:51]
	ds_write_b32 v154, v20
.LBB0_322:
	s_or_b64 exec, exec, s[40:41]
	s_waitcnt lgkmcnt(0)
	s_barrier
	ds_read_b128 v[34:37], v219
	ds_read_b128 v[18:21], v219 offset:16
	ds_read_b64 v[22:23], v219 offset:32
	v_lshlrev_b32_e32 v38, 16, v190
	v_and_b32_e32 v39, 0xffff0000, v190
	s_waitcnt lgkmcnt(2)
	v_mov_b32_e32 v32, v34
	s_waitcnt lgkmcnt(1)
	v_mov_b32_e32 v33, v18
	v_lshlrev_b32_e32 v40, 16, v192
	v_and_b32_e32 v41, 0xffff0000, v192
	s_waitcnt lgkmcnt(0)
	v_fma_f32 v38, v32, v38, v22
	v_fma_f32 v39, v33, v39, v23
	v_mov_b32_e32 v18, v35
	v_lshlrev_b32_e32 v42, 16, v252
	v_and_b32_e32 v43, 0xffff0000, v252
	v_fma_f32 v38, v18, v40, v38
	v_fma_f32 v39, v19, v41, v39
	v_mov_b32_e32 v34, v36
	v_mov_b32_e32 v35, v20
	s_waitcnt vmcnt(8)
	v_lshlrev_b32_e32 v44, 16, v251
	v_and_b32_e32 v45, 0xffff0000, v251
	v_fma_f32 v38, v34, v42, v38
	v_fma_f32 v39, v35, v43, v39
	v_mov_b32_e32 v20, v37
	v_fma_f32 v36, v20, v44, v38
	v_fma_f32 v37, v21, v45, v39
	s_mov_b32 s40, 0xbfb8aa3b
	v_mul_f32_e32 v38, s40, v36
	v_mul_f32_e32 v39, s40, v37
	v_lshlrev_b32_e32 v46, 16, v0
	v_exp_f32_e32 v38, v38
	v_exp_f32_e32 v39, v39
	v_and_b32_e32 v47, 0xffff0000, v0
	v_lshlrev_b32_e32 v48, 16, v123
	v_and_b32_e32 v49, 0xffff0000, v123
	v_add_f32_e32 v38, 1.0, v38
	v_add_f32_e32 v39, 1.0, v39
	v_lshlrev_b32_e32 v82, 16, v246
	v_rcp_f32_e32 v38, v38
	v_rcp_f32_e32 v39, v39
	v_and_b32_e32 v83, 0xffff0000, v246
	v_lshlrev_b32_e32 v24, 16, v247
	v_and_b32_e32 v25, 0xffff0000, v247
	v_mul_f32_e32 v36, v36, v38
	v_mul_f32_e32 v37, v37, v39
	ds_read2_b32 v[38:39], v147 offset1:1
	ds_read2_b32 v[84:85], v147 offset0:2 offset1:3
	ds_read2_b32 v[86:87], v147 offset0:4 offset1:5
	v_cvt_pk_bf16_f32 v88, v36, v37
	v_lshlrev_b32_e32 v28, 16, v248
	s_waitcnt lgkmcnt(2)
	v_mul_f32_e32 v36, v38, v36
	v_mul_f32_e32 v37, v38, v37
	v_cvt_pk_bf16_f32 v36, v36, v37
	ds_write2_b32 v220, v88, v36 offset1:32
	v_fma_f32 v36, v32, v40, v22
	v_fma_f32 v37, v33, v41, v23
	v_mov_b32_e32 v38, v39
	v_fma_f32 v36, v18, v42, v36
	v_fma_f32 v37, v19, v43, v37
	v_and_b32_e32 v29, 0xffff0000, v248
	v_fma_f32 v36, v34, v44, v36
	v_fma_f32 v37, v35, v45, v37
	v_lshlrev_b32_e32 v30, 16, v249
	v_fma_f32 v36, v20, v46, v36
	v_fma_f32 v37, v21, v47, v37
	v_and_b32_e32 v31, 0xffff0000, v249
	v_mul_f32_e32 v40, s40, v36
	v_mul_f32_e32 v41, s40, v37
	v_lshlrev_b32_e32 v26, 16, v250
	v_exp_f32_e32 v40, v40
	v_exp_f32_e32 v41, v41
	v_and_b32_e32 v27, 0xffff0000, v250
	s_add_i32 s33, s44, 1
	s_cmp_lg_u32 s44, 31
	v_add_f32_e32 v40, 1.0, v40
	v_add_f32_e32 v41, 1.0, v41
	s_nop 0
	v_rcp_f32_e32 v40, v40
	v_rcp_f32_e32 v41, v41
	s_nop 0
	v_mul_f32_e32 v36, v36, v40
	v_mul_f32_e32 v37, v37, v41
	s_nop 0
	v_cvt_pk_bf16_f32 v40, v36, v37
	v_mul_f32_e32 v36, v38, v36
	v_mul_f32_e32 v37, v38, v37
	v_cvt_pk_bf16_f32 v36, v36, v37
	ds_write2_b32 v220, v40, v36 offset0:68 offset1:100
	v_fma_f32 v36, v32, v42, v22
	v_fma_f32 v37, v33, v43, v23
	s_nop 0
	v_fma_f32 v36, v18, v44, v36
	v_fma_f32 v37, v19, v45, v37
	s_nop 0
	v_fma_f32 v36, v34, v46, v36
	v_fma_f32 v37, v35, v47, v37
	s_nop 0
	v_fma_f32 v36, v20, v48, v36
	v_fma_f32 v37, v21, v49, v37
	s_nop 0
	v_mul_f32_e32 v38, s40, v36
	v_mul_f32_e32 v39, s40, v37
	s_nop 0
	v_exp_f32_e32 v38, v38
	v_exp_f32_e32 v39, v39
	s_nop 0
	v_add_f32_e32 v38, 1.0, v38
	v_add_f32_e32 v39, 1.0, v39
	s_nop 0
	v_rcp_f32_e32 v38, v38
	v_rcp_f32_e32 v39, v39
	s_nop 0
	v_mul_f32_e32 v36, v36, v38
	v_mul_f32_e32 v37, v37, v39
	s_nop 0
	v_cvt_pk_bf16_f32 v38, v36, v37
	s_waitcnt lgkmcnt(3)
	v_mul_f32_e32 v36, v84, v36
	v_mul_f32_e32 v37, v84, v37
	v_cvt_pk_bf16_f32 v36, v36, v37
	ds_write2_b32 v220, v38, v36 offset0:136 offset1:168
	v_fma_f32 v36, v32, v44, v22
	v_fma_f32 v37, v33, v45, v23
	s_nop 0
	v_fma_f32 v36, v18, v46, v36
	v_fma_f32 v37, v19, v47, v37
	s_nop 0
	v_fma_f32 v36, v34, v48, v36
	v_fma_f32 v37, v35, v49, v37
	s_nop 0
	v_fma_f32 v36, v20, v82, v36
	v_fma_f32 v37, v21, v83, v37
	s_nop 0
	v_mul_f32_e32 v38, s40, v36
	v_mul_f32_e32 v39, s40, v37
	s_nop 0
	v_exp_f32_e32 v38, v38
	v_exp_f32_e32 v39, v39
	s_nop 0
	v_add_f32_e32 v38, 1.0, v38
	v_add_f32_e32 v39, 1.0, v39
	s_nop 0
	v_rcp_f32_e32 v38, v38
	v_rcp_f32_e32 v39, v39
	s_nop 0
	v_mul_f32_e32 v36, v36, v38
	v_mul_f32_e32 v37, v37, v39
	v_mov_b32_e32 v38, v85
	v_cvt_pk_bf16_f32 v39, v36, v37
	s_nop 0
	v_mul_f32_e32 v36, v36, v38
	v_mul_f32_e32 v37, v37, v38
	s_nop 0
	v_cvt_pk_bf16_f32 v36, v36, v37
	ds_write2_b32 v220, v39, v36 offset0:204 offset1:236
	v_fma_f32 v36, v32, v46, v22
	v_fma_f32 v37, v33, v47, v23
	s_nop 0
	v_fma_f32 v36, v18, v48, v36
	v_fma_f32 v37, v19, v49, v37
	s_nop 0
	v_fma_f32 v36, v34, v82, v36
	v_fma_f32 v37, v35, v83, v37
	s_nop 0
	v_fma_f32 v36, v20, v24, v36
	v_fma_f32 v37, v21, v25, v37
	s_nop 0
	v_mul_f32_e32 v38, s40, v36
	v_mul_f32_e32 v39, s40, v37
	s_nop 0
	v_exp_f32_e32 v38, v38
	v_exp_f32_e32 v39, v39
	s_nop 0
	v_add_f32_e32 v38, 1.0, v38
	v_add_f32_e32 v39, 1.0, v39
	s_nop 0
	v_rcp_f32_e32 v38, v38
	v_rcp_f32_e32 v39, v39
	s_nop 0
	v_mul_f32_e32 v36, v36, v38
	v_mul_f32_e32 v37, v37, v39
	s_nop 0
	v_cvt_pk_bf16_f32 v39, v36, v37
	s_waitcnt lgkmcnt(4)
	v_mul_f32_e32 v36, v36, v86
	v_mul_f32_e32 v37, v37, v86
	v_add_u32_e32 v38, 0x400, v220
	v_cvt_pk_bf16_f32 v36, v36, v37
	ds_write2_b32 v38, v39, v36 offset0:16 offset1:48
	v_fma_f32 v36, v32, v48, v22
	v_fma_f32 v37, v33, v49, v23
	s_nop 0
	v_fma_f32 v36, v18, v82, v36
	v_fma_f32 v37, v19, v83, v37
	s_nop 0
	v_fma_f32 v36, v34, v24, v36
	v_fma_f32 v37, v35, v25, v37
	s_nop 0
	v_fma_f32 v36, v20, v28, v36
	v_fma_f32 v37, v21, v29, v37
	s_nop 0
	v_mul_f32_e32 v40, s40, v36
	v_mul_f32_e32 v41, s40, v37
	s_nop 0
	v_exp_f32_e32 v40, v40
	v_exp_f32_e32 v41, v41
	s_nop 0
	v_add_f32_e32 v40, 1.0, v40
	v_add_f32_e32 v41, 1.0, v41
	s_nop 0
	v_rcp_f32_e32 v40, v40
	v_rcp_f32_e32 v41, v41
	s_nop 0
	v_mul_f32_e32 v36, v36, v40
	v_mul_f32_e32 v37, v37, v41
	v_mov_b32_e32 v40, v87
	v_cvt_pk_bf16_f32 v39, v36, v37
	v_mul_f32_e32 v36, v36, v40
	v_mul_f32_e32 v37, v37, v40
	s_nop 0
	v_cvt_pk_bf16_f32 v36, v36, v37
	ds_write2_b32 v38, v39, v36 offset0:84 offset1:116
	v_fma_f32 v36, v32, v82, v22
	v_fma_f32 v37, v33, v83, v23
	v_fma_f32 v22, v32, v24, v22
	v_fma_f32 v23, v33, v25, v23
	v_fma_f32 v36, v18, v24, v36
	v_fma_f32 v37, v19, v25, v37
	v_fma_f32 v18, v18, v28, v22
	v_fma_f32 v19, v19, v29, v23
	v_fma_f32 v36, v34, v28, v36
	v_fma_f32 v37, v35, v29, v37
	v_fma_f32 v18, v34, v30, v18
	v_fma_f32 v19, v35, v31, v19
	v_fma_f32 v36, v20, v30, v36
	v_fma_f32 v37, v21, v31, v37
	v_fma_f32 v18, v20, v26, v18
	v_fma_f32 v19, v21, v27, v19
	v_mul_f32_e32 v40, s40, v36
	v_mul_f32_e32 v41, s40, v37
	v_mul_f32_e32 v20, s40, v18
	v_mul_f32_e32 v21, s40, v19
	v_exp_f32_e32 v40, v40
	v_exp_f32_e32 v41, v41
	v_exp_f32_e32 v20, v20
	v_exp_f32_e32 v21, v21
	s_cselect_b64 s[40:41], -1, 0
	v_add_f32_e32 v40, 1.0, v40
	v_add_f32_e32 v41, 1.0, v41
	s_and_b64 vcc, s[8:9], s[40:41]
	v_rcp_f32_e32 v40, v40
	v_rcp_f32_e32 v41, v41
	v_add_f32_e32 v20, 1.0, v20
	v_add_f32_e32 v21, 1.0, v21
	v_mul_f32_e32 v40, v36, v40
	v_mul_f32_e32 v41, v37, v41
	ds_read2_b32 v[36:37], v147 offset0:6 offset1:7
	v_rcp_f32_e32 v20, v20
	v_rcp_f32_e32 v21, v21
	v_cvt_pk_bf16_f32 v39, v40, v41
	s_waitcnt lgkmcnt(0)
	v_mul_f32_e32 v40, v40, v36
	v_mul_f32_e32 v41, v41, v36
	v_mul_f32_e32 v18, v18, v20
	v_mul_f32_e32 v19, v19, v21
	v_mov_b32_e32 v20, v37
	v_cvt_pk_bf16_f32 v21, v18, v19
	v_cvt_pk_bf16_f32 v36, v40, v41
	ds_write2_b32 v38, v39, v36 offset0:152 offset1:184
	v_mul_f32_e32 v18, v18, v20
	v_mul_f32_e32 v19, v19, v20
	s_nop 0
	v_cvt_pk_bf16_f32 v18, v18, v19
	ds_write2_b32 v38, v21, v18 offset0:220 offset1:252
	s_cmp_eq_u32 s33, 1
	s_cbranch_scc1 .Lssd_c_first
	s_waitcnt vmcnt(4)
	s_branch .Lssd_c_w

.LBB0_324:
	s_or_b64 exec, exec, s[42:43]
	v_lshl_or_b32 v18, s44, 7, v155
	v_or_b32_e32 v144, s34, v18
	s_movk_i32 s37, 0x1e00
	v_mad_u64_u32 v[18:19], s[42:43], v144, s37, v[132:133]
	v_mad_i32_i24 v19, s35, v199, v19
	global_load_dwordx2 v[142:143], v[18:19], off
	global_load_dwordx2 v[140:141], v[18:19], off offset:16
	global_load_dwordx2 v[138:139], v[18:19], off offset:32
	global_load_dwordx2 v[136:137], v[18:19], off offset:48
	s_waitcnt lgkmcnt(0)
	s_barrier
	v_add_u32_e32 v196, 0x19800, v222
	ds_read_b32 v163, v156
	ds_read_b128 v[18:21], v196
	v_add_u32_e32 v191, 0x11000, v241
	ds_read_b128 v[34:37], v191
	ds_read_b128 v[38:41], v196 offset:32
	ds_read_b128 v[90:93], v191 offset:32
	ds_read_b128 v[200:203], v196 offset:64
	ds_read_b128 v[106:109], v191 offset:64
	ds_read_b128 v[94:97], v191 offset:96
	ds_read_b128 v[102:105], v191 offset:128
	ds_read_b128 v[86:89], v191 offset:160
	ds_read_b128 v[98:101], v191 offset:192
	ds_read_b128 v[82:85], v191 offset:224
	v_mov_b32_e32 v145, s35
	s_waitcnt lgkmcnt(9)
	v_mfma_f32_32x32x16_bf16 v[18:33], v[18:21], v[34:37], 0
	s_waitcnt lgkmcnt(7)
	v_mfma_f32_32x32x16_bf16 v[18:33], v[38:41], v[90:93], v[18:33]
	ds_read_b128 v[38:41], v196 offset:96
	s_waitcnt lgkmcnt(6)
	v_mfma_f32_32x32x16_bf16 v[18:33], v[200:203], v[106:109], v[18:33]
	ds_read_b128 v[200:203], v196 offset:128
	s_waitcnt lgkmcnt(1)
	v_mfma_f32_32x32x16_bf16 v[18:33], v[38:41], v[94:97], v[18:33]
	ds_read_b128 v[38:41], v196 offset:160
	s_waitcnt lgkmcnt(1)
	v_mfma_f32_32x32x16_bf16 v[18:33], v[200:203], v[102:105], v[18:33]
	ds_read_b128 v[200:203], v196 offset:192
	s_waitcnt lgkmcnt(1)
	v_mfma_f32_32x32x16_bf16 v[18:33], v[38:41], v[86:89], v[18:33]
	ds_read_b128 v[38:41], v196 offset:224
	s_waitcnt lgkmcnt(1)
	v_mfma_f32_32x32x16_bf16 v[18:33], v[200:203], v[98:101], v[18:33]
	s_waitcnt lgkmcnt(0)
	v_mfma_f32_32x32x16_bf16 v[18:33], v[38:41], v[82:85], v[18:33]
	ds_read_b32 v38, v157
	s_waitcnt lgkmcnt(0)
	s_nop 9
	v_mul_f32_e32 v32, v38, v32
	v_mul_f32_e32 v33, v38, v33
	v_mul_f32_e32 v30, v38, v30
	v_mul_f32_e32 v31, v38, v31
	v_mul_f32_e32 v28, v38, v28
	v_mul_f32_e32 v29, v38, v29
	v_mul_f32_e32 v26, v38, v26
	v_mul_f32_e32 v27, v38, v27
	v_mul_f32_e32 v24, v38, v24
	v_mul_f32_e32 v25, v38, v25
	v_mul_f32_e32 v22, v38, v22
	v_mul_f32_e32 v23, v38, v23
	v_mul_f32_e32 v20, v38, v20
	v_mul_f32_e32 v21, v38, v21
	v_mul_f32_e32 v18, v38, v18
	v_mul_f32_e32 v19, v38, v19
	s_mov_b64 s[42:43], exec
	v_readlane_b32 s44, v254, 20
	v_readlane_b32 s45, v254, 21
	s_and_b64 s[44:45], s[42:43], s[44:45]
	s_mov_b64 exec, s[44:45]
	s_cbranch_execz .LBB0_328
	s_mov_b32 s37, 0
	s_mov_b64 s[44:45], 0
	v_mov_b32_e32 v82, v217
	v_mov_b32_e32 v83, v216
	v_mov_b32_e32 v84, v215
	v_mov_b32_e32 v85, v158

.LBB0_328:
	s_or_b64 exec, exec, s[42:43]
	ds_read_b128 v[38:41], v241 offset:34816
	ds_read_b128 v[164:167], v241 offset:34848
	ds_read_b128 v[200:203], v241 offset:34880
	s_waitcnt lgkmcnt(2)
	v_mfma_f32_32x32x16_bf16 v[34:49], v[38:41], v[34:37], 0
	s_waitcnt lgkmcnt(1)
	v_mfma_f32_32x32x16_bf16 v[34:49], v[164:167], v[90:93], v[34:49]
	ds_read_b128 v[90:93], v241 offset:34912
	ds_read_b128 v[164:167], v241 offset:34944
	s_waitcnt lgkmcnt(2)
	v_mfma_f32_32x32x16_bf16 v[34:49], v[200:203], v[106:109], v[34:49]
	ds_read_b128 v[200:203], v241 offset:34976
	s_waitcnt lgkmcnt(2)
	v_mfma_f32_32x32x16_bf16 v[34:49], v[90:93], v[94:97], v[34:49]
	ds_read_b128 v[90:93], v241 offset:35008
	s_waitcnt lgkmcnt(2)
	v_mfma_f32_32x32x16_bf16 v[34:49], v[164:167], v[102:105], v[34:49]
	ds_read_b128 v[164:167], v241 offset:35040
	s_waitcnt lgkmcnt(2)
	v_mfma_f32_32x32x16_bf16 v[34:49], v[200:203], v[86:89], v[34:49]
	s_waitcnt lgkmcnt(1)
	v_mfma_f32_32x32x16_bf16 v[34:49], v[90:93], v[98:101], v[34:49]
	s_waitcnt lgkmcnt(0)
	v_mfma_f32_32x32x16_bf16 v[34:49], v[164:167], v[82:85], v[34:49]
	v_mov_b32_e32 v82, v163
	s_mov_b64 s[42:43], exec
	v_readlane_b32 s44, v254, 62
	v_readlane_b32 s45, v254, 63
	s_and_b64 s[44:45], s[42:43], s[44:45]
	s_mov_b64 exec, s[44:45]
	ds_read_b32 v82, v160
	s_mov_b64 exec, s[42:43]
	ds_read_b32 v83, v161
	v_mov_b32_e32 v85, v163
	s_and_saveexec_b64 s[42:43], s[38:39]
	ds_read_b32 v85, v168
	s_mov_b64 exec, s[42:43]
	ds_read_b32 v86, v169
	v_mov_b32_e32 v84, v163
	s_mov_b64 s[42:43], exec
	v_readlane_b32 s44, v255, 6
	v_readlane_b32 s45, v255, 7
	s_and_b64 s[44:45], s[42:43], s[44:45]
	s_mov_b64 exec, s[44:45]
	ds_read_b32 v84, v170
	s_mov_b64 exec, s[42:43]
	ds_read_b32 v87, v171
	v_mov_b32_e32 v89, v163
	s_mov_b64 s[42:43], exec
	v_readlane_b32 s44, v255, 12
	v_readlane_b32 s45, v255, 13
	s_and_b64 s[44:45], s[42:43], s[44:45]
	s_mov_b64 exec, s[44:45]
	ds_read_b32 v89, v172
	s_mov_b64 exec, s[42:43]
	ds_read_b32 v88, v173
	v_mov_b32_e32 v90, v163
	s_and_saveexec_b64 s[42:43], s[56:57]
	ds_read_b32 v90, v174
	s_mov_b64 exec, s[42:43]
	ds_read_b32 v91, v175
	v_mov_b32_e32 v93, v163
	s_and_saveexec_b64 s[42:43], s[62:63]
	ds_read_b32 v93, v176
	s_mov_b64 exec, s[42:43]
	ds_read_b32 v92, v177
	v_mov_b32_e32 v94, v163
	s_and_saveexec_b64 s[42:43], s[68:69]
	ds_read_b32 v94, v178
	s_mov_b64 exec, s[42:43]
	ds_read_b32 v96, v179
	v_mov_b32_e32 v98, v163
	s_and_saveexec_b64 s[42:43], s[74:75]
	ds_read_b32 v98, v180
	s_mov_b64 exec, s[42:43]
	ds_read_b32 v97, v181
	v_mov_b32_e32 v99, v163
	s_and_saveexec_b64 s[42:43], s[80:81]
	ds_read_b32 v99, v182
	s_mov_b64 exec, s[42:43]
	ds_read_b32 v100, v183
	v_mov_b32_e32 v102, v163
	s_and_saveexec_b64 s[42:43], s[86:87]
	ds_read_b32 v102, v184
	s_mov_b64 exec, s[42:43]
	ds_read_b32 v101, v185
	v_mov_b32_e32 v103, v163
	s_and_saveexec_b64 s[42:43], s[92:93]
	ds_read_b32 v103, v186
	s_mov_b64 exec, s[42:43]
	ds_read_b32 v104, v187
	v_mov_b32_e32 v106, v163
	s_and_saveexec_b64 s[42:43], s[2:3]
	ds_read_b32 v106, v188
	s_mov_b64 exec, s[42:43]
	ds_read_b32 v105, v189
	v_mov_b32_e32 v107, v163
	s_and_saveexec_b64 s[42:43], s[0:1]
	ds_read_b32 v107, v204
	s_mov_b64 exec, s[42:43]
	ds_read_b32 v108, v205
	v_mov_b32_e32 v109, v163
	s_and_saveexec_b64 s[42:43], s[14:15]
	ds_read_b32 v109, v206
	s_mov_b64 exec, s[42:43]
	ds_read_b32 v191, v207
	v_mov_b32_e32 v193, v163
	s_and_saveexec_b64 s[42:43], s[22:23]
	ds_read_b32 v193, v208
	s_mov_b64 exec, s[42:43]
	ds_read_b32 v164, v209
	v_mov_b32_e32 v95, v163
	s_and_saveexec_b64 s[42:43], s[28:29]
	ds_read_b32 v95, v210
	s_mov_b64 exec, s[42:43]
	s_waitcnt lgkmcnt(0)
	v_sub_f32_e32 v82, v163, v82
	v_sub_f32_e32 v85, v163, v85
	v_sub_f32_e32 v84, v163, v84
	v_sub_f32_e32 v89, v163, v89
	v_sub_f32_e32 v90, v163, v90
	v_sub_f32_e32 v93, v163, v93
	v_sub_f32_e32 v94, v163, v94
	v_sub_f32_e32 v98, v163, v98
	v_sub_f32_e32 v99, v163, v99
	v_sub_f32_e32 v102, v163, v102
	v_sub_f32_e32 v103, v163, v103
	v_sub_f32_e32 v106, v163, v106
	v_sub_f32_e32 v107, v163, v107
	v_sub_f32_e32 v109, v163, v109
	v_sub_f32_e32 v193, v163, v193
	v_sub_f32_e32 v95, v163, v95
	v_exp_f32_e32 v106, v106
	v_readlane_b32 s42, v255, 10
	v_readlane_b32 s43, v255, 11
	v_exp_f32_e32 v163, v193
	v_mul_f32_e32 v45, v45, v106
	s_waitcnt lgkmcnt(3)
	v_mul_f32_e32 v45, v105, v45
	v_cndmask_b32_e64 v45, v45, 0, s[96:97]
	v_add_f32_e32 v105, v243, v45
	v_cndmask_b32_e64 v105, v45, v105, s[4:5]
	v_exp_f32_e32 v45, v103
	v_exp_f32_e32 v109, v109
	v_exp_f32_e32 v107, v107
	v_mul_f32_e32 v48, v48, v163
	v_mul_f32_e32 v44, v44, v45
	v_mul_f32_e32 v44, v104, v44
	v_cndmask_b32_e64 v44, v44, 0, s[90:91]
	v_add_f32_e32 v45, v243, v44
	v_cndmask_b32_e64 v103, v44, v45, s[94:95]
	v_exp_f32_e32 v44, v102
	v_mul_f32_e32 v47, v47, v109
	v_mul_f32_e32 v46, v46, v107
	s_waitcnt lgkmcnt(0)
	v_mul_f32_e32 v48, v164, v48
	v_mul_f32_e32 v43, v43, v44
	v_mul_f32_e32 v43, v101, v43
	v_cndmask_b32_e64 v43, v43, 0, s[84:85]
	v_add_f32_e32 v44, v243, v43
	v_cndmask_b32_e64 v101, v43, v44, s[88:89]
	v_exp_f32_e32 v43, v99
	v_mul_f32_e32 v47, v191, v47
	v_mul_f32_e32 v46, v108, v46
	v_cndmask_b32_e64 v48, v48, 0, s[20:21]
	v_mul_f32_e32 v42, v42, v43
	v_mul_f32_e32 v42, v100, v42
	v_cndmask_b32_e64 v42, v42, 0, s[78:79]
	v_add_f32_e32 v43, v243, v42
	v_cndmask_b32_e64 v99, v42, v43, s[82:83]
	v_exp_f32_e32 v42, v98
	ds_read_b32 v43, v211
	v_cndmask_b32_e64 v47, v47, 0, s[10:11]
	v_cndmask_b32_e64 v46, v46, 0, s[6:7]
	v_mul_f32_e32 v41, v41, v42
	v_mul_f32_e32 v41, v97, v41
	v_cndmask_b32_e64 v41, v41, 0, s[72:73]
	v_add_f32_e32 v42, v243, v41
	v_cndmask_b32_e64 v41, v41, v42, s[76:77]
	v_exp_f32_e32 v42, v94
	v_add_f32_e32 v163, v243, v48
	v_add_f32_e32 v109, v243, v47
	v_add_f32_e32 v107, v243, v46
	v_mul_f32_e32 v40, v40, v42
	v_mul_f32_e32 v40, v96, v40
	v_cndmask_b32_e64 v40, v40, 0, s[66:67]
	v_add_f32_e32 v42, v243, v40
	v_cndmask_b32_e64 v40, v40, v42, s[70:71]
	v_exp_f32_e32 v42, v93
	v_readlane_b32 s37, v253, 48
	v_cndmask_b32_e64 v48, v48, v163, s[24:25]
	v_cndmask_b32_e64 v47, v47, v109, s[18:19]
	v_mul_f32_e32 v39, v39, v42
	v_mul_f32_e32 v39, v92, v39
	v_cndmask_b32_e64 v39, v39, 0, s[60:61]
	v_add_f32_e32 v42, v243, v39
	v_cndmask_b32_e64 v39, v39, v42, s[64:65]
	v_exp_f32_e32 v42, v90
	v_cndmask_b32_e64 v46, v46, v107, s[12:13]
	v_cvt_pk_bf16_f32 v45, v40, v41
	s_andn2_b64 vcc, exec, s[40:41]
	v_mul_f32_e32 v38, v38, v42
	v_mul_f32_e32 v38, v91, v38
	v_cndmask_b32_e64 v38, v38, 0, s[54:55]
	v_add_f32_e32 v42, v243, v38
	v_cndmask_b32_e64 v38, v38, v42, s[58:59]
	v_exp_f32_e32 v42, v89
	v_cvt_pk_bf16_f32 v44, v38, v39
	v_add_u32_e32 v38, 0, v159
	v_mul_f32_e32 v37, v37, v42
	v_mul_f32_e32 v37, v88, v37
	v_cndmask_b32_e64 v37, v37, 0, s[42:43]
	v_readlane_b32 s42, v255, 14
	v_add_f32_e32 v42, v243, v37
	v_readlane_b32 s43, v255, 15
	s_nop 1
	v_cndmask_b32_e64 v37, v37, v42, s[42:43]
	v_exp_f32_e32 v42, v84
	v_readlane_b32 s42, v255, 4
	v_readlane_b32 s43, v255, 5
	v_mul_f32_e32 v36, v36, v42
	v_mul_f32_e32 v36, v87, v36
	v_cndmask_b32_e64 v36, v36, 0, s[42:43]
	v_readlane_b32 s42, v255, 8
	v_add_f32_e32 v42, v243, v36
	v_readlane_b32 s43, v255, 9
	s_nop 1
	v_cndmask_b32_e64 v36, v36, v42, s[42:43]
	v_exp_f32_e32 v42, v85
	v_readlane_b32 s42, v255, 2
	v_readlane_b32 s43, v255, 3
	v_mul_f32_e32 v35, v35, v42
	v_mul_f32_e32 v35, v86, v35
	v_cndmask_b32_e64 v35, 0, v35, s[38:39]
	v_add_f32_e32 v42, v243, v35
	v_cndmask_b32_e64 v35, v35, v42, s[42:43]
	v_exp_f32_e32 v42, v82
	v_readlane_b32 s42, v254, 60
	v_readlane_b32 s43, v254, 61
	v_mov_b32_e32 v82, s37
	v_mul_f32_e32 v34, v34, v42
	v_mul_f32_e32 v34, v83, v34
	v_cndmask_b32_e64 v34, v34, 0, s[42:43]
	v_readlane_b32 s42, v255, 0
	v_add_f32_e32 v42, v243, v34
	v_readlane_b32 s43, v255, 1
	s_nop 1
	v_cndmask_b32_e64 v34, v34, v42, s[42:43]
	v_exp_f32_e32 v42, v95
	s_nop 0
	v_mul_f32_e32 v42, v49, v42
	s_waitcnt lgkmcnt(0)
	v_mul_f32_e32 v42, v43, v42
	v_cndmask_b32_e64 v42, v42, 0, s[26:27]
	v_add_f32_e32 v43, v243, v42
	v_cndmask_b32_e64 v49, v42, v43, s[16:17]
	v_cvt_pk_bf16_f32 v43, v36, v37
	v_cvt_pk_bf16_f32 v36, v46, v47
	v_cvt_pk_bf16_f32 v37, v48, v49
	ds_read_b64_tr_b16 v[46:47], v38
	ds_read_b64_tr_b16 v[48:49], v38 offset:2176
	ds_read_b64_tr_b16 v[38:39], v223
	ds_read_b64_tr_b16 v[40:41], v223 offset:2176
	ds_read_b32 v82, v82
	v_cvt_pk_bf16_f32 v42, v34, v35
	v_cvt_pk_bf16_f32 v34, v99, v101
	v_cvt_pk_bf16_f32 v35, v103, v105
	s_waitcnt lgkmcnt(0)
	v_mul_f32_e32 v16, v16, v82
	v_mul_f32_e32 v17, v17, v82
	v_mul_f32_e32 v14, v14, v82
	v_mul_f32_e32 v15, v15, v82
	v_mul_f32_e32 v12, v12, v82
	v_mul_f32_e32 v13, v13, v82
	v_mul_f32_e32 v10, v10, v82
	v_mul_f32_e32 v11, v11, v82
	v_mul_f32_e32 v8, v8, v82
	v_mul_f32_e32 v9, v9, v82
	v_mul_f32_e32 v6, v6, v82
	v_mul_f32_e32 v7, v7, v82
	v_mul_f32_e32 v4, v4, v82
	v_mul_f32_e32 v5, v5, v82
	v_mul_f32_e32 v2, v2, v82
	v_mul_f32_e32 v3, v3, v82
	ds_read_b64_tr_b16 v[82:83], v224 offset:128
	ds_read_b64_tr_b16 v[84:85], v224 offset:2304
	ds_read_b64_tr_b16 v[86:87], v225 offset:34816
	ds_read_b64_tr_b16 v[88:89], v225 offset:36992
	ds_read_b64_tr_b16 v[90:91], v226 offset:128
	ds_read_b64_tr_b16 v[92:93], v226 offset:2304
	ds_read_b64_tr_b16 v[98:99], v227 offset:34816
	ds_read_b64_tr_b16 v[100:101], v227 offset:36992
	ds_read_b64_tr_b16 v[94:95], v228 offset:128
	ds_read_b64_tr_b16 v[96:97], v228 offset:2304
	ds_read_b64_tr_b16 v[102:103], v229 offset:34816
	ds_read_b64_tr_b16 v[104:105], v229 offset:36992
	s_waitcnt lgkmcnt(8)
	v_mfma_f32_32x32x16_bf16 v[2:17], v[82:85], v[86:89], v[2:17]
	ds_read_b64_tr_b16 v[82:83], v230 offset:128
	ds_read_b64_tr_b16 v[84:85], v230 offset:2304
	ds_read_b64_tr_b16 v[86:87], v231 offset:34816
	ds_read_b64_tr_b16 v[88:89], v231 offset:36992
	s_waitcnt lgkmcnt(8)
	v_mfma_f32_32x32x16_bf16 v[2:17], v[90:93], v[98:101], v[2:17]
	ds_read_b64_tr_b16 v[90:91], v232 offset:128
	ds_read_b64_tr_b16 v[92:93], v232 offset:2304
	ds_read_b64_tr_b16 v[98:99], v233 offset:34816
	ds_read_b64_tr_b16 v[100:101], v233 offset:36992
	s_waitcnt lgkmcnt(8)
	v_mfma_f32_32x32x16_bf16 v[2:17], v[94:97], v[102:105], v[2:17]
	ds_read_b64_tr_b16 v[94:95], v234 offset:128
	ds_read_b64_tr_b16 v[96:97], v234 offset:2304
	ds_read_b64_tr_b16 v[102:103], v235 offset:34816
	ds_read_b64_tr_b16 v[104:105], v235 offset:36992
	s_waitcnt lgkmcnt(8)
	v_mfma_f32_32x32x16_bf16 v[2:17], v[82:85], v[86:89], v[2:17]
	ds_read_b64_tr_b16 v[82:83], v236 offset:128
	ds_read_b64_tr_b16 v[84:85], v236 offset:2304
	ds_read_b64_tr_b16 v[86:87], v237 offset:34816
	ds_read_b64_tr_b16 v[88:89], v237 offset:36992
	s_waitcnt lgkmcnt(8)
	v_mfma_f32_32x32x16_bf16 v[2:17], v[90:93], v[98:101], v[2:17]
	ds_read_b64_tr_b16 v[90:91], v238 offset:128
	ds_read_b64_tr_b16 v[92:93], v238 offset:2304
	ds_read_b64_tr_b16 v[98:99], v239 offset:34816
	ds_read_b64_tr_b16 v[100:101], v239 offset:36992
	s_waitcnt lgkmcnt(8)
	v_mfma_f32_32x32x16_bf16 v[2:17], v[94:97], v[102:105], v[2:17]
	s_waitcnt lgkmcnt(4)
	v_mfma_f32_32x32x16_bf16 v[2:17], v[82:85], v[86:89], v[2:17]
	s_waitcnt lgkmcnt(0)
	s_barrier
	v_mfma_f32_32x32x16_bf16 v[18:33], v[46:49], v[42:45], v[18:33]
	s_waitcnt lgkmcnt(0)
	v_mfma_f32_32x32x16_bf16 v[2:17], v[90:93], v[98:101], v[2:17]
	v_mfma_f32_32x32x16_bf16 v[18:33], v[38:41], v[34:37], v[18:33]
	s_cbranch_vccnz .LBB0_314
	v_readlane_b32 s40, v254, 14
	v_readlane_b32 s41, v254, 15
	s_mov_b32 s43, s41
	s_lshl_b32 s42, s33, 7
	v_lshl_add_u64 v[34:35], s[42:43], 0, v[112:113]
	s_movk_i32 s37, 0x1e00
	v_mad_u64_u32 v[36:37], s[40:41], v34, s37, v[124:125]
	v_mad_i32_i24 v37, v35, s37, v37
	v_add_co_u32_e32 v34, vcc, 0xffffb000, v36
	s_movk_i32 s37, 0x2000
	s_nop 0
	v_addc_co_u32_e32 v35, vcc, -1, v37, vcc
	v_add_co_u32_e32 v38, vcc, 0xffffd000, v36
	s_lshl_b32 s42, s33, 17
	s_nop 0
	v_addc_co_u32_e32 v39, vcc, -1, v37, vcc
	v_add_co_u32_e32 v40, vcc, 0xfffff000, v36
	s_nop 1
	v_addc_co_u32_e32 v41, vcc, -1, v37, vcc
	v_add_co_u32_e32 v42, vcc, s37, v36
	s_movk_i32 s37, 0x4000
	s_nop 0
	v_addc_co_u32_e32 v43, vcc, 0, v37, vcc
	v_add_co_u32_e32 v44, vcc, s37, v36
	s_movk_i32 s37, 0x6000
	s_nop 0
	v_addc_co_u32_e32 v45, vcc, 0, v37, vcc
	v_add_co_u32_e32 v46, vcc, s37, v36
	s_mov_b32 s37, 0x8000
	s_nop 0
	v_addc_co_u32_e32 v47, vcc, 0, v37, vcc
	v_add_co_u32_e32 v48, vcc, s37, v36
	s_mov_b32 s37, 0x9000
	s_nop 0
	v_addc_co_u32_e32 v49, vcc, 0, v37, vcc
	v_add_co_u32_e32 v50, vcc, s37, v36
	s_mov_b32 s37, s43
	s_nop 0
	v_addc_co_u32_e32 v51, vcc, 0, v37, vcc
	global_load_dword v190, v[34:35], off offset:-512
	global_load_dword v192, v[38:39], off offset:-1024
	global_load_dword v252, v[40:41], off offset:-1536
	global_load_dword v0, v[42:43], off offset:1536
	global_load_dword v123, v[44:45], off offset:1024
	global_load_dword v246, v[46:47], off offset:512
	global_load_dword v247, v[48:49], off
	global_load_dword v248, v[50:51], off offset:3584
	v_add_co_u32_e32 v34, vcc, 0xb000, v36
	v_lshl_add_u64 v[40:41], v[126:127], 0, s[42:43]
	s_nop 0
	v_addc_co_u32_e32 v35, vcc, 0, v37, vcc
	v_add_co_u32_e32 v38, vcc, 0xd000, v36
	v_writelane_b32 v254, s36, 14
	s_nop 0
	v_addc_co_u32_e32 v39, vcc, 0, v37, vcc
	global_load_dword v249, v[34:35], off offset:3072
	global_load_dword v250, v[38:39], off offset:2560
	global_load_dwordx4 v[50:53], v[40:41], off
	v_add_co_u32_e32 v34, vcc, 0x4000, v40
	v_writelane_b32 v254, s37, 15
	s_nop 0
	v_addc_co_u32_e32 v35, vcc, 0, v41, vcc
	v_add_co_u32_e32 v38, vcc, 0x8000, v40
	s_nop 1
	v_addc_co_u32_e32 v39, vcc, 0, v41, vcc
	global_load_dwordx4 v[54:57], v[34:35], off
	global_load_dwordx4 v[58:61], v[38:39], off
	v_add_co_u32_e32 v34, vcc, 0xc000, v40
	s_nop 1
	v_addc_co_u32_e32 v35, vcc, 0, v41, vcc
	v_add_co_u32_e32 v38, vcc, 0x10000, v40
	s_nop 1
	v_addc_co_u32_e32 v39, vcc, 0, v41, vcc
	global_load_dwordx4 v[62:65], v[34:35], off
	global_load_dwordx4 v[66:69], v[38:39], off
	v_add_co_u32_e32 v34, vcc, 0x14000, v40
	s_nop 1
	v_addc_co_u32_e32 v35, vcc, 0, v41, vcc
	v_add_co_u32_e32 v38, vcc, 0x18000, v40
	s_nop 1
	v_addc_co_u32_e32 v39, vcc, 0, v41, vcc
	global_load_dwordx4 v[70:73], v[34:35], off
	global_load_dwordx4 v[74:77], v[38:39], off
	v_add_co_u32_e32 v34, vcc, 0x1c000, v40
	s_nop 1
	v_addc_co_u32_e32 v35, vcc, 0, v41, vcc
	global_load_dword v251, v[36:37], off offset:2048
	global_load_dwordx4 v[78:81], v[34:35], off
	s_branch .LBB0_314
